# hand-written stick-breaking attention tile loop (next-tile K/V prefetch, log2-domain softplus, half the VALU)
# baseline (speedup 1.0000x reference)
; __global__ void __launch_bounds__(NTHR, 2) fwd_kernel(Args args) {
;     ...
;                     const int bh = task >> 8, qb = task & 255, b = bh >> 4, hd = bh & 15, t0 = qb * 32;
;                     const bf16_t* qp = Q + ((size_t)(b * SEQ + t0 + r)) * D + hd * 64 + 8 * hh;
;                     bf16x8 qr[4];
; #pragma unroll
;                     for (int d0 = 0; d0 < 4; ++d0) qr[d0] = *(const bf16x8*)(qp + 16 * d0);
;                     f32x16 o0, o1;
; #pragma unroll
;                     for (int i = 0; i < 16; ++i) { o0[i] = 0.f; o1[i] = 0.f; }
;                     float R = 0.f;
;                     const bf16_t* kbase = Kb + ((size_t)b * SEQ + pir) * D + hd * 64 + 8 * hh;
;                     const bf16_t* vbase = VT + ((size_t)(bh * 64 + r)) * SEQ + 16 * hh;
;                     bf16x8 kf[4], va[2][2];
;     ...
;                     ATT_LOAD(kf, va, qb);
;                     bf16x8 kfn[4], van[2][2];
;                     ATT_LOAD(kfn, van, qb > 0 ? qb - 1 : 0);
; #pragma nounroll
;     ...
;                         bf16x8 kf2[4], va2[2][2];
;                         ATT_LOAD(kf2, va2, kt > 1 ? kt - 2 : 0);
;                         f32x16 Sx;
; #pragma unroll
;                         for (int i = 0; i < 16; ++i) Sx[i] = 0.f;
; #pragma unroll
;                         for (int d0 = 0; d0 < 4; ++d0) Sx = __builtin_amdgcn_mfma_f32_32x32x16_bf16(kf[d0], qr[d0], Sx, 0, 0, 0);
.LBB0_170:
	s_and_b32 s23, s13, 0xff
	s_ashr_i32 s2, s13, 12
	s_lshl_b32 s70, s23, 5
	s_lshl_b32 s3, s2, 13
	s_or_b32 s22, s3, s70
	v_or_b32_e32 v0, s22, v80
	v_ashrrev_i32_e32 v1, 31, v0
	v_readlane_b32 s26, v255, 10
	v_lshlrev_b64 v[0:1], 11, v[0:1]
	v_readlane_b32 s27, v255, 11
	s_ashr_i32 s3, s13, 2
	v_mov_b32_e32 v87, v169
	v_lshl_add_u64 v[0:1], s[26:27], 0, v[0:1]
	s_and_b32 s26, s3, 0x3c0
	s_lshl_b32 s4, s26, 1
	v_lshl_add_u64 v[0:1], v[0:1], 0, s[4:5]
	v_lshl_add_u64 v[0:1], v[0:1], 0, v[86:87]
	global_load_dwordx4 v[48:51], v[0:1], off
	global_load_dwordx4 v[52:55], v[0:1], off offset:32
	global_load_dwordx4 v[56:59], v[0:1], off offset:64
	global_load_dwordx4 v[60:63], v[0:1], off offset:96
	s_and_b32 s14, s3, 0xffffffc0
	s_ashr_i32 s3, s2, 31
	s_lshl_b64 s[2:3], s[2:3], 24
	v_lshl_add_u64 v[0:1], v[82:83], 0, s[2:3]
	v_lshl_add_u64 v[0:1], v[0:1], 0, s[4:5]
	v_lshl_add_u64 v[90:91], v[0:1], 0, v[86:87]
	v_or_b32_e32 v0, s14, v80
	v_ashrrev_i32_e32 v1, 31, v0
	v_lshlrev_b64 v[0:1], 14, v[0:1]
	s_mov_b32 s71, s5
	v_lshl_add_u64 v[92:93], v[84:85], 0, v[0:1]
	v_sub_u32_e64 v0, s23, 1 clamp
	v_mov_b32_e32 v87, 0
	v_lshlrev_b32_e32 v32, 5, v0
	v_mov_b32_e32 v33, v169
	s_mov_b32 s4, 0
	v_mov_b64_e32 v[94:95], s[70:71]
	v_mov_b32_e32 v0, 0
	v_mov_b32_e32 v1, v87
	v_mov_b32_e32 v2, v87
	v_mov_b32_e32 v3, v87
	s_waitcnt vmcnt(4)
	v_mov_b32_e32 v4, v87
	v_mov_b32_e32 v5, v87
	v_mov_b32_e32 v6, v87
	v_mov_b32_e32 v7, v87
	v_mov_b32_e32 v8, v87
	v_mov_b32_e32 v9, v87
	v_mov_b32_e32 v10, v87
	v_mov_b32_e32 v11, v87
	v_mov_b32_e32 v12, v87
	v_mov_b32_e32 v13, v87
	v_mov_b32_e32 v14, v87
	v_mov_b32_e32 v15, v87
	v_mov_b32_e32 v16, 0
	v_mov_b32_e32 v17, v87
	v_mov_b32_e32 v18, v87
	v_mov_b32_e32 v19, v87
	v_mov_b32_e32 v20, v87
	v_mov_b32_e32 v21, v87
	v_mov_b32_e32 v22, v87
	v_mov_b32_e32 v23, v87
	v_mov_b32_e32 v24, v87
	v_mov_b32_e32 v25, v87
	v_mov_b32_e32 v26, v87
	v_mov_b32_e32 v27, v87
	v_mov_b32_e32 v28, v87
	v_mov_b32_e32 v29, v87
	v_mov_b32_e32 v30, v87
	v_mov_b32_e32 v31, v87
	v_lshl_add_u64 v[154:155], v[94:95], 1, v[92:93]
	v_lshlrev_b64 v[158:159], 11, v[94:95]
	v_add_co_u32_e32 v156, vcc, 0x80000, v154
	v_lshl_add_u64 v[158:159], v[90:91], 0, v[158:159]
	s_nop 0
	v_addc_co_u32_e32 v157, vcc, 0, v155, vcc
	global_load_dwordx4 v[204:207], v[158:159], off
	global_load_dwordx4 v[208:211], v[158:159], off offset:32
	global_load_dwordx4 v[212:215], v[158:159], off offset:64
	global_load_dwordx4 v[216:219], v[158:159], off offset:96
	global_load_dwordx4 v[220:223], v[154:155], off
	global_load_dwordx4 v[224:227], v[154:155], off offset:16
	global_load_dwordx4 v[228:231], v[156:157], off
	global_load_dwordx4 v[232:235], v[156:157], off offset:16
.LBB0_171:
	v_mov_b64_e32 v[152:153], v[32:33]
	s_waitcnt vmcnt(0)
	v_mov_b64_e32 v[236:237], v[204:205]
	v_mov_b64_e32 v[238:239], v[206:207]
	v_mov_b64_e32 v[240:241], v[208:209]
	v_mov_b64_e32 v[242:243], v[210:211]
	v_mov_b64_e32 v[244:245], v[212:213]
	v_mov_b64_e32 v[246:247], v[214:215]
	v_mov_b64_e32 v[132:133], v[216:217]
	v_mov_b64_e32 v[134:135], v[218:219]
	v_mov_b64_e32 v[136:137], v[220:221]
	v_mov_b64_e32 v[138:139], v[222:223]
	v_mov_b64_e32 v[140:141], v[224:225]
	v_mov_b64_e32 v[142:143], v[226:227]
	v_mov_b64_e32 v[144:145], v[228:229]
	v_mov_b64_e32 v[146:147], v[230:231]
	v_mov_b64_e32 v[148:149], v[232:233]
	v_mov_b64_e32 v[150:151], v[234:235]
	v_mov_b64_e32 v[94:95], v[152:153]
	s_nop 0
	v_mfma_f32_32x32x16_bf16 v[32:47], v[236:239], v[48:51], 0
	v_mfma_f32_32x32x16_bf16 v[32:47], v[240:243], v[52:55], v[32:47]
	v_mfma_f32_32x32x16_bf16 v[32:47], v[244:247], v[56:59], v[32:47]
	v_mfma_f32_32x32x16_bf16 v[32:47], v[132:135], v[60:63], v[32:47]
	v_lshl_add_u64 v[154:155], v[152:153], 1, v[92:93]
	v_lshlrev_b64 v[158:159], 11, v[152:153]
	v_add_co_u32_e32 v156, vcc, 0x80000, v154
	v_lshl_add_u64 v[158:159], v[90:91], 0, v[158:159]
	s_nop 0
	v_addc_co_u32_e32 v157, vcc, 0, v155, vcc
	global_load_dwordx4 v[204:207], v[158:159], off
	global_load_dwordx4 v[208:211], v[158:159], off offset:32
	global_load_dwordx4 v[212:215], v[158:159], off offset:64
	global_load_dwordx4 v[216:219], v[158:159], off offset:96
	global_load_dwordx4 v[220:223], v[154:155], off
	global_load_dwordx4 v[224:227], v[154:155], off offset:16
	global_load_dwordx4 v[228:231], v[156:157], off
	global_load_dwordx4 v[232:235], v[156:157], off offset:16
	s_cmp_lg_u32 s4, 0
	s_nop 1
	s_cbranch_scc1 .Lattn_nodiag
	v_cndmask_b32_e64 v32, v200, v32, s[38:39]
	v_cndmask_b32_e64 v33, v200, v33, s[40:41]
	v_cndmask_b32_e64 v34, v200, v34, s[42:43]
	v_cndmask_b32_e64 v35, v200, v35, s[44:45]
	v_cndmask_b32_e64 v36, v200, v36, s[46:47]
	v_cndmask_b32_e64 v37, v200, v37, s[48:49]
	v_cndmask_b32_e64 v38, v200, v38, s[50:51]
	v_cndmask_b32_e64 v39, v200, v39, s[52:53]
	v_cndmask_b32_e64 v40, v200, v40, s[54:55]
	v_cndmask_b32_e64 v41, v200, v41, s[56:57]
	v_cndmask_b32_e64 v42, v200, v42, s[58:59]
	v_cndmask_b32_e64 v43, v200, v43, s[60:61]
	v_cndmask_b32_e64 v44, v200, v44, s[62:63]
	v_cndmask_b32_e64 v45, v200, v45, s[64:65]
	v_cndmask_b32_e64 v46, v200, v46, s[66:67]
	v_cndmask_b32_e64 v47, v200, v47, s[68:69]
; __device__ __forceinline__ unsigned pk2(float lo, float hi) { f32x2_t v = {lo, hi}; bf16x2_t b = __builtin_convertvector(v, bf16x2_t); return __builtin_bit_cast(unsigned, b); }
; __device__ __forceinline__ float shx(float v, int mask, int lane) { return __int_as_float(__builtin_amdgcn_ds_bpermute((lane ^ mask) << 2, __float_as_int(v))); }
; __device__ __forceinline__ float softplusf_(float z) { return fmaxf(z, 0.f) + __logf(1.f + __expf(-fabsf(z))); }
; __global__ void __launch_bounds__(NTHR, 2) fwd_kernel(Args args) {
;     ...
;                         const bool diag = (kt == qb);
;                         float lk[16];
; #pragma unroll
;                         for (int i = 0; i < 16; ++i) { const bool valid = !diag || (16 * hh + i < r); const float z = Sx[i]; const float sp = softplusf_(z);
;                             lk[i] = valid ? -sp : 0.f; Sx[i] = valid ? z - sp : -1e30f; }
;                         float ex[16], run = 0.f;
; #pragma unroll
;                         for (int i = 15; i >= 0; --i) { ex[i] = run; run += lk[i]; }
;                         const float other = shx(run, 32, lane);
;                         const float wb = R + (hh == 0 ? other : 0.f);
;                         u32x4 pw[2];
; #pragma unroll
;                         for (int q4 = 0; q4 < 4; ++q4) {
;                             const float e0 = __expf(Sx[4 * q4] + (wb + ex[4 * q4])), e1 = __expf(Sx[4 * q4 + 1] + (wb + ex[4 * q4 + 1])), e2 = __expf(Sx[4 * q4 + 2] + (wb + ex[4 * q4 + 2])), e3 = __expf(Sx[4 * q4 + 3] + (wb + ex[4 * q4 + 3]));
;                             pw[q4 >> 1][(q4 & 1) * 2] = pk2(e0, e1); pw[q4 >> 1][(q4 & 1) * 2 + 1] = pk2(e2, e3);
;                         }
;                         R += run + other;
; #pragma unroll
;                         for (int s = 0; s < 2; ++s) {
;                             const bf16x8 pa = __builtin_bit_cast(bf16x8, pw[s]);
;                             o0 = __builtin_amdgcn_mfma_f32_32x32x16_bf16(pa, va[0][s], o0, 0, 0, 0);
;                             o1 = __builtin_amdgcn_mfma_f32_32x32x16_bf16(pa, va[1][s], o1, 0, 0, 0);
;                         }
;                         if (__all(R < -104.f)) break;
.Lattn_nodiag:
	v_mul_f32_e64 v96, |v32|, s79
	v_mul_f32_e64 v97, |v33|, s79
	v_mul_f32_e64 v98, |v34|, s79
	v_mul_f32_e64 v99, |v35|, s79
	v_mul_f32_e64 v100, |v36|, s79
	v_mul_f32_e64 v101, |v37|, s79
	v_mul_f32_e64 v102, |v38|, s79
	v_mul_f32_e64 v103, |v39|, s79
	v_mul_f32_e64 v104, |v40|, s79
	v_mul_f32_e64 v105, |v41|, s79
	v_mul_f32_e64 v106, |v42|, s79
	v_mul_f32_e64 v107, |v43|, s79
	v_mul_f32_e64 v108, |v44|, s79
	v_mul_f32_e64 v109, |v45|, s79
	v_mul_f32_e64 v110, |v46|, s79
	v_mul_f32_e64 v111, |v47|, s79
	v_exp_f32_e32 v96, v96
	v_exp_f32_e32 v97, v97
	v_exp_f32_e32 v98, v98
	v_exp_f32_e32 v99, v99
	v_exp_f32_e32 v100, v100
	v_exp_f32_e32 v101, v101
	v_exp_f32_e32 v102, v102
	v_exp_f32_e32 v103, v103
	v_exp_f32_e32 v104, v104
	v_exp_f32_e32 v105, v105
	v_exp_f32_e32 v106, v106
	v_exp_f32_e32 v107, v107
	v_exp_f32_e32 v108, v108
	v_exp_f32_e32 v109, v109
	v_exp_f32_e32 v110, v110
	v_exp_f32_e32 v111, v111
	v_add_f32_e32 v96, 1.0, v96
	v_add_f32_e32 v97, 1.0, v97
	v_add_f32_e32 v98, 1.0, v98
	v_add_f32_e32 v99, 1.0, v99
	v_add_f32_e32 v100, 1.0, v100
	v_add_f32_e32 v101, 1.0, v101
	v_add_f32_e32 v102, 1.0, v102
	v_add_f32_e32 v103, 1.0, v103
	v_add_f32_e32 v104, 1.0, v104
	v_add_f32_e32 v105, 1.0, v105
	v_add_f32_e32 v106, 1.0, v106
	v_add_f32_e32 v107, 1.0, v107
	v_add_f32_e32 v108, 1.0, v108
	v_add_f32_e32 v109, 1.0, v109
	v_add_f32_e32 v110, 1.0, v110
	v_add_f32_e32 v111, 1.0, v111
	v_log_f32_e32 v96, v96
	v_log_f32_e32 v97, v97
	v_log_f32_e32 v98, v98
	v_log_f32_e32 v99, v99
	v_log_f32_e32 v100, v100
	v_log_f32_e32 v101, v101
	v_log_f32_e32 v102, v102
	v_log_f32_e32 v103, v103
	v_log_f32_e32 v104, v104
	v_log_f32_e32 v105, v105
	v_log_f32_e32 v106, v106
	v_log_f32_e32 v107, v107
	v_log_f32_e32 v108, v108
	v_log_f32_e32 v109, v109
	v_log_f32_e32 v110, v110
	v_log_f32_e32 v111, v111
	v_max_f32_e32 v112, 0, v32
	v_fmac_f32_e32 v96, 0x3fb8aa3b, v112
	v_max_f32_e32 v112, 0, v33
	v_fmac_f32_e32 v97, 0x3fb8aa3b, v112
	v_max_f32_e32 v112, 0, v34
	v_fmac_f32_e32 v98, 0x3fb8aa3b, v112
	v_max_f32_e32 v112, 0, v35
	v_fmac_f32_e32 v99, 0x3fb8aa3b, v112
	v_max_f32_e32 v112, 0, v36
	v_fmac_f32_e32 v100, 0x3fb8aa3b, v112
	v_max_f32_e32 v112, 0, v37
	v_fmac_f32_e32 v101, 0x3fb8aa3b, v112
	v_max_f32_e32 v112, 0, v38
	v_fmac_f32_e32 v102, 0x3fb8aa3b, v112
	v_max_f32_e32 v112, 0, v39
	v_fmac_f32_e32 v103, 0x3fb8aa3b, v112
	v_max_f32_e32 v112, 0, v40
	v_fmac_f32_e32 v104, 0x3fb8aa3b, v112
	v_max_f32_e32 v112, 0, v41
	v_fmac_f32_e32 v105, 0x3fb8aa3b, v112
	v_max_f32_e32 v112, 0, v42
	v_fmac_f32_e32 v106, 0x3fb8aa3b, v112
	v_max_f32_e32 v112, 0, v43
	v_fmac_f32_e32 v107, 0x3fb8aa3b, v112
	v_max_f32_e32 v112, 0, v44
	v_fmac_f32_e32 v108, 0x3fb8aa3b, v112
	v_max_f32_e32 v112, 0, v45
	v_fmac_f32_e32 v109, 0x3fb8aa3b, v112
	v_max_f32_e32 v112, 0, v46
	v_fmac_f32_e32 v110, 0x3fb8aa3b, v112
	v_max_f32_e32 v112, 0, v47
	v_fmac_f32_e32 v111, 0x3fb8aa3b, v112
	v_fma_f32 v32, v32, s79, v96
	v_fma_f32 v33, v33, s79, v97
	v_fma_f32 v34, v34, s79, v98
	v_fma_f32 v35, v35, s79, v99
	v_fma_f32 v36, v36, s79, v100
	v_fma_f32 v37, v37, s79, v101
	v_fma_f32 v38, v38, s79, v102
	v_fma_f32 v39, v39, s79, v103
	v_fma_f32 v40, v40, s79, v104
	v_fma_f32 v41, v41, s79, v105
	v_fma_f32 v42, v42, s79, v106
	v_fma_f32 v43, v43, s79, v107
	v_fma_f32 v44, v44, s79, v108
	v_fma_f32 v45, v45, s79, v109
	v_fma_f32 v46, v46, s79, v110
	v_fma_f32 v47, v47, s79, v111
	v_mov_b32_e32 v128, v111
	v_add_f32_e32 v127, v128, v110
	v_add_f32_e32 v126, v127, v109
	v_add_f32_e32 v125, v126, v108
	v_add_f32_e32 v124, v125, v107
	v_add_f32_e32 v123, v124, v106
	v_add_f32_e32 v122, v123, v105
	v_add_f32_e32 v121, v122, v104
	v_add_f32_e32 v120, v121, v103
	v_add_f32_e32 v119, v120, v102
	v_add_f32_e32 v118, v119, v101
	v_add_f32_e32 v117, v118, v100
	v_add_f32_e32 v116, v117, v99
	v_add_f32_e32 v115, v116, v98
	v_add_f32_e32 v114, v115, v97
	v_add_f32_e32 v113, v114, v96
	ds_bpermute_b32 v129, v81, v113
	v_add_f32_e32 v32, v114, v32
	v_add_f32_e32 v33, v115, v33
	v_add_f32_e32 v34, v116, v34
	v_add_f32_e32 v35, v117, v35
	v_add_f32_e32 v36, v118, v36
	v_add_f32_e32 v37, v119, v37
	v_add_f32_e32 v38, v120, v38
	v_add_f32_e32 v39, v121, v39
	v_add_f32_e32 v40, v122, v40
	v_add_f32_e32 v41, v123, v41
	v_add_f32_e32 v42, v124, v42
	v_add_f32_e32 v43, v125, v43
	v_add_f32_e32 v44, v126, v44
	v_add_f32_e32 v45, v127, v45
	v_add_f32_e32 v46, v128, v46
	s_mov_b64 s[70:71], -1
	s_mov_b64 s[74:75], -1
	s_waitcnt lgkmcnt(0)
	v_cndmask_b32_e64 v130, 0, v129, s[36:37]
	v_sub_f32_e32 v130, v87, v130
	v_sub_f32_e32 v32, v130, v32
	v_sub_f32_e32 v33, v130, v33
	v_sub_f32_e32 v34, v130, v34
	v_sub_f32_e32 v35, v130, v35
	v_sub_f32_e32 v36, v130, v36
	v_sub_f32_e32 v37, v130, v37
	v_sub_f32_e32 v38, v130, v38
	v_sub_f32_e32 v39, v130, v39
	v_sub_f32_e32 v40, v130, v40
	v_sub_f32_e32 v41, v130, v41
	v_sub_f32_e32 v42, v130, v42
	v_sub_f32_e32 v43, v130, v43
	v_sub_f32_e32 v44, v130, v44
	v_sub_f32_e32 v45, v130, v45
	v_sub_f32_e32 v46, v130, v46
	v_sub_f32_e32 v47, v130, v47
	v_exp_f32_e32 v32, v32
	v_exp_f32_e32 v33, v33
	v_exp_f32_e32 v34, v34
	v_exp_f32_e32 v35, v35
	v_exp_f32_e32 v36, v36
	v_exp_f32_e32 v37, v37
	v_exp_f32_e32 v38, v38
	v_exp_f32_e32 v39, v39
	v_exp_f32_e32 v40, v40
	v_exp_f32_e32 v41, v41
	v_exp_f32_e32 v42, v42
	v_exp_f32_e32 v43, v43
	v_exp_f32_e32 v44, v44
	v_exp_f32_e32 v45, v45
	v_exp_f32_e32 v46, v46
	v_exp_f32_e32 v47, v47
	v_add_f32_e32 v131, v113, v129
	v_sub_f32_e32 v87, v87, v131
	s_mov_b32 s2, 0xc3160a50
	v_cvt_pk_bf16_f32 v160, v32, v33
	v_cvt_pk_bf16_f32 v161, v34, v35
	v_cvt_pk_bf16_f32 v162, v36, v37
	v_cvt_pk_bf16_f32 v163, v38, v39
	v_cvt_pk_bf16_f32 v164, v40, v41
	v_cvt_pk_bf16_f32 v165, v42, v43
	v_cvt_pk_bf16_f32 v166, v44, v45
	v_cvt_pk_bf16_f32 v167, v46, v47
	v_cmp_gt_f32_e32 vcc, s2, v87
	s_cmp_lg_u64 vcc, exec
	v_mfma_f32_32x32x16_bf16 v[0:15], v[160:163], v[136:139], v[0:15]
	v_mfma_f32_32x32x16_bf16 v[16:31], v[160:163], v[144:147], v[16:31]
	v_mfma_f32_32x32x16_bf16 v[0:15], v[164:167], v[140:143], v[0:15]
	v_mfma_f32_32x32x16_bf16 v[16:31], v[164:167], v[148:151], v[16:31]
	s_cbranch_scc0 .LBB0_173
	s_max_u32 s2, s23, 2
	s_lshl_b32 s2, s2, 5
	s_sub_i32 s2, s2, 64
	s_ashr_i32 s3, s2, 31
	s_add_i32 s23, s23, -1
	s_add_i32 s4, s4, 1
	s_cmp_eq_u32 s23, -1
	s_mov_b64 s[70:71], 0
	s_cselect_b64 s[74:75], -1, 0
